# G1: last tile of each step stores write-through (sc1) so the grid barrier's release flush has nothing left to write back
# baseline (speedup 1.0000x reference)
; #define PG8_STAGE(bufoff, gbase, voff) do { _Pragma("unroll") for (int _i = 0; _i < 2; ++_i) \
;         __builtin_amdgcn_global_load_lds((const unsigned*)((const char*)(gbase) + (voff)[_i]), (LAS unsigned*)(lds + (bufoff) + ldsw + _i * 8192), 16, 0, 0); } while (0)
; #define PG8_LDA(dst, b, h) do { _Pragma("unroll") for (int m = 0; m < 4; ++m) _Pragma("unroll") for (int k = 0; k < 2; ++k) dst[m][k] = *(const LAS bf16x8*)(lds + PG8_SA(b, h) + aoff + m * 2048 + k * 1024); } while (0)
; #define PG8_LDB(dst, b, h) do { _Pragma("unroll") for (int n = 0; n < 2; ++n) _Pragma("unroll") for (int k = 0; k < 2; ++k) dst[n][k] = *(const LAS bf16x8*)(lds + PG8_SB(b, h) + boff + n * 2048 + k * 1024); } while (0)
; #define PG8_MMA(ai, bj, At, Bt) do { __builtin_amdgcn_s_setprio(1); _Pragma("unroll") for (int m = 0; m < 4; ++m) _Pragma("unroll") for (int n = 0; n < 2; ++n) _Pragma("unroll") for (int k = 0; k < 2; ++k) \
;         acc[ai][bj][m][n] = __builtin_amdgcn_mfma_f32_16x16x32_bf16(Bt[n][k], At[m][k], acc[ai][bj][m][n], 0, 0, 0); __builtin_amdgcn_s_setprio(0); } while (0)
; #define PG8_WAIT_V(n) asm volatile("s_waitcnt vmcnt(" #n ")" ::: "memory")
; #define PG8_WAIT_L(n) asm volatile("s_waitcnt lgkmcnt(" #n ")" ::: "memory")
; #define PG8_BAR __builtin_amdgcn_s_barrier()
; #define PG8_SCHED __builtin_amdgcn_sched_barrier(0)
; template <class Epi, class Sched>
; DI void gemm_phase(ldsp lds, const Gemm g, const Sched& S, const Epi& E, const int tid) {
;     ...
;             PG8_LDB(B0, 0, 0); PG8_SCHED; PG8_LDA(At, 0, 0); PG8_STAGE(PG8_SA(1, 1), a1 + hstep, voffA);
;             PG8_WAIT_L(8); PG8_BAR; PG8_WAIT_L(0); PG8_MMA(0, 0, At, B0); PG8_BAR; PG8_SCHED;
;             PG8_LDB(B1, 0, 1); PG8_STAGE(PG8_SB(0, 0), b2, voffB);
;             PG8_BAR; PG8_WAIT_L(0); PG8_MMA(0, 1, At, B1); PG8_BAR;
;             PG8_LDA(At, 0, 1); PG8_STAGE(PG8_SA(0, 0), a2, voffA);
;             PG8_BAR; PG8_WAIT_L(0); PG8_MMA(1, 0, At, B0); PG8_BAR; PG8_SCHED;
;             PG8_STAGE(PG8_SB(0, 1), b2 + hstep, voffB);
;             PG8_WAIT_V(6); PG8_BAR; PG8_MMA(1, 1, At, B1); PG8_BAR;
.LBB0_663:
	s_add_u32 s48, s46, 0xfffc0080
	s_addc_u32 s49, s47, -1
	s_add_i32 s72, 0, 0x10000
	v_add_u32_e32 v156, s72, v33
	ds_read_b128 v[146:149], v156
	ds_read_b128 v[150:153], v156 offset:1024
	ds_read_b128 v[162:165], v156 offset:2048
	ds_read_b128 v[166:169], v156 offset:3072
	s_cmp_eq_u32 s69, 12
	s_cselect_b32 s51, s41, s49
	s_cselect_b32 s50, s65, s48
	s_cselect_b32 s49, s37, s68
	s_cselect_b32 s48, s66, s67
	v_lshl_add_u64 v[158:159], s[46:47], 0, v[140:141]
	s_add_i32 m0, s31, 0xc000
	ds_read_b128 v[170:173], v145
	ds_read_b128 v[174:177], v145 offset:1024
	ds_read_b128 v[178:181], v145 offset:2048
	ds_read_b128 v[182:185], v145 offset:3072
	ds_read_b128 v[186:189], v145 offset:4096
	ds_read_b128 v[190:193], v145 offset:5120
	ds_read_b128 v[194:197], v145 offset:6144
	ds_read_b128 v[198:201], v145 offset:7168
	global_load_lds_dwordx4 v[158:159], off
	v_lshl_add_u64 v[158:159], s[46:47], 0, v[142:143]
	s_add_i32 m0, s31, 0xe000
	s_nop 0
	global_load_lds_dwordx4 v[158:159], off
	s_waitcnt lgkmcnt(8)
	s_barrier
	s_waitcnt lgkmcnt(0)
	s_setprio 1
	s_waitcnt lgkmcnt(0)
	v_mfma_f32_16x16x32_bf16 v[130:133], v[146:149], v[170:173], v[130:133]
	v_mfma_f32_16x16x32_bf16 v[126:129], v[162:165], v[170:173], v[126:129]
	v_mfma_f32_16x16x32_bf16 v[122:125], v[146:149], v[178:181], v[122:125]
	v_mfma_f32_16x16x32_bf16 v[118:121], v[162:165], v[178:181], v[118:121]
	v_mfma_f32_16x16x32_bf16 v[106:109], v[146:149], v[186:189], v[106:109]
	v_mfma_f32_16x16x32_bf16 v[102:105], v[162:165], v[186:189], v[102:105]
	v_mfma_f32_16x16x32_bf16 v[90:93], v[146:149], v[194:197], v[90:93]
	v_mfma_f32_16x16x32_bf16 v[86:89], v[162:165], v[194:197], v[86:89]
	v_mfma_f32_16x16x32_bf16 v[130:133], v[150:153], v[174:177], v[130:133]
	v_mfma_f32_16x16x32_bf16 v[126:129], v[166:169], v[174:177], v[126:129]
	v_mfma_f32_16x16x32_bf16 v[122:125], v[150:153], v[182:185], v[122:125]
	v_mfma_f32_16x16x32_bf16 v[118:121], v[166:169], v[182:185], v[118:121]
	v_mfma_f32_16x16x32_bf16 v[106:109], v[150:153], v[190:193], v[106:109]
	v_mfma_f32_16x16x32_bf16 v[102:105], v[166:169], v[190:193], v[102:105]
	v_mfma_f32_16x16x32_bf16 v[90:93], v[150:153], v[198:201], v[90:93]
	v_mfma_f32_16x16x32_bf16 v[86:89], v[166:169], v[198:201], v[86:89]
	s_setprio 0
	s_barrier
	s_add_i32 s74, 0, 0x14000
	s_add_i32 s72, s72, s35
	v_add_u32_e32 v156, s74, v33
	v_lshl_add_u64 v[158:159], s[48:49], 0, v[136:137]
	s_mov_b32 m0, s72
	ds_read_b128 v[202:205], v156
	ds_read_b128 v[206:209], v156 offset:1024
	ds_read_b128 v[210:213], v156 offset:2048
	ds_read_b128 v[214:217], v156 offset:3072
	global_load_lds_dwordx4 v[158:159], off
	v_lshl_add_u64 v[160:161], s[48:49], 0, v[30:31]
	s_add_i32 m0, s72, 0x2000
	s_nop 0
	global_load_lds_dwordx4 v[160:161], off
	s_barrier
	s_waitcnt lgkmcnt(0)
	s_setprio 1
	s_waitcnt lgkmcnt(0)
	v_mfma_f32_16x16x32_bf16 v[114:117], v[202:205], v[170:173], v[114:117]
	v_mfma_f32_16x16x32_bf16 v[110:113], v[210:213], v[170:173], v[110:113]
	v_mfma_f32_16x16x32_bf16 v[98:101], v[202:205], v[178:181], v[98:101]
	v_mfma_f32_16x16x32_bf16 v[94:97], v[210:213], v[178:181], v[94:97]
	v_mfma_f32_16x16x32_bf16 v[82:85], v[202:205], v[186:189], v[82:85]
	v_mfma_f32_16x16x32_bf16 v[78:81], v[210:213], v[186:189], v[78:81]
	v_mfma_f32_16x16x32_bf16 v[74:77], v[202:205], v[194:197], v[74:77]
	v_mfma_f32_16x16x32_bf16 v[70:73], v[210:213], v[194:197], v[70:73]
	v_mfma_f32_16x16x32_bf16 v[114:117], v[206:209], v[174:177], v[114:117]
	v_mfma_f32_16x16x32_bf16 v[110:113], v[214:217], v[174:177], v[110:113]
	v_mfma_f32_16x16x32_bf16 v[98:101], v[206:209], v[182:185], v[98:101]
	v_mfma_f32_16x16x32_bf16 v[94:97], v[214:217], v[182:185], v[94:97]
	v_mfma_f32_16x16x32_bf16 v[82:85], v[206:209], v[190:193], v[82:85]
	v_mfma_f32_16x16x32_bf16 v[78:81], v[214:217], v[190:193], v[78:81]
	v_mfma_f32_16x16x32_bf16 v[74:77], v[206:209], v[198:201], v[74:77]
	v_mfma_f32_16x16x32_bf16 v[70:73], v[214:217], v[198:201], v[70:73]
	s_setprio 0
	s_mov_b32 m0, s31
	v_lshl_add_u64 v[218:219], s[50:51], 0, v[138:139]
	s_barrier
	ds_read_b128 v[170:173], v145 offset:16384
	ds_read_b128 v[174:177], v145 offset:17408
	ds_read_b128 v[178:181], v145 offset:18432
	ds_read_b128 v[182:185], v145 offset:19456
	ds_read_b128 v[186:189], v145 offset:20480
	ds_read_b128 v[190:193], v145 offset:21504
	ds_read_b128 v[194:197], v145 offset:22528
	ds_read_b128 v[198:201], v145 offset:23552
	global_load_lds_dwordx4 v[218:219], off
	v_lshl_add_u64 v[220:221], s[50:51], 0, v[134:135]
	s_mov_b32 m0, s58
	s_nop 0
	global_load_lds_dwordx4 v[220:221], off
	s_barrier
	s_waitcnt lgkmcnt(0)
	s_setprio 1
	s_waitcnt lgkmcnt(0)
	v_mfma_f32_16x16x32_bf16 v[66:69], v[146:149], v[170:173], v[66:69]
	v_mfma_f32_16x16x32_bf16 v[62:65], v[162:165], v[170:173], v[62:65]
	v_mfma_f32_16x16x32_bf16 v[58:61], v[146:149], v[178:181], v[58:61]
	v_mfma_f32_16x16x32_bf16 v[54:57], v[162:165], v[178:181], v[54:57]
	v_mfma_f32_16x16x32_bf16 v[42:45], v[146:149], v[186:189], v[42:45]
	v_mfma_f32_16x16x32_bf16 v[38:41], v[162:165], v[186:189], v[38:41]
	v_mfma_f32_16x16x32_bf16 v[22:25], v[146:149], v[194:197], v[22:25]
	v_mfma_f32_16x16x32_bf16 v[18:21], v[162:165], v[194:197], v[18:21]
	v_mfma_f32_16x16x32_bf16 v[66:69], v[150:153], v[174:177], v[66:69]
	v_mfma_f32_16x16x32_bf16 v[62:65], v[166:169], v[174:177], v[62:65]
	v_mfma_f32_16x16x32_bf16 v[58:61], v[150:153], v[182:185], v[58:61]
	v_mfma_f32_16x16x32_bf16 v[54:57], v[166:169], v[182:185], v[54:57]
	v_mfma_f32_16x16x32_bf16 v[42:45], v[150:153], v[190:193], v[42:45]
	v_mfma_f32_16x16x32_bf16 v[38:41], v[166:169], v[190:193], v[38:41]
	v_mfma_f32_16x16x32_bf16 v[22:25], v[150:153], v[198:201], v[22:25]
	v_mfma_f32_16x16x32_bf16 v[18:21], v[166:169], v[198:201], v[18:21]
	s_setprio 0
	s_barrier
; #define PG8_STAGE(bufoff, gbase, voff) do { _Pragma("unroll") for (int _i = 0; _i < 2; ++_i) \
;         __builtin_amdgcn_global_load_lds((const unsigned*)((const char*)(gbase) + (voff)[_i]), (LAS unsigned*)(lds + (bufoff) + ldsw + _i * 8192), 16, 0, 0); } while (0)
; #define PG8_LDA(dst, b, h) do { _Pragma("unroll") for (int m = 0; m < 4; ++m) _Pragma("unroll") for (int k = 0; k < 2; ++k) dst[m][k] = *(const LAS bf16x8*)(lds + PG8_SA(b, h) + aoff + m * 2048 + k * 1024); } while (0)
; #define PG8_LDB(dst, b, h) do { _Pragma("unroll") for (int n = 0; n < 2; ++n) _Pragma("unroll") for (int k = 0; k < 2; ++k) dst[n][k] = *(const LAS bf16x8*)(lds + PG8_SB(b, h) + boff + n * 2048 + k * 1024); } while (0)
; #define PG8_MMA(ai, bj, At, Bt) do { __builtin_amdgcn_s_setprio(1); _Pragma("unroll") for (int m = 0; m < 4; ++m) _Pragma("unroll") for (int n = 0; n < 2; ++n) _Pragma("unroll") for (int k = 0; k < 2; ++k) \
;         acc[ai][bj][m][n] = __builtin_amdgcn_mfma_f32_16x16x32_bf16(Bt[n][k], At[m][k], acc[ai][bj][m][n], 0, 0, 0); __builtin_amdgcn_s_setprio(0); } while (0)
; #define PG8_WAIT_V(n) asm volatile("s_waitcnt vmcnt(" #n ")" ::: "memory")
; #define PG8_WAIT_L(n) asm volatile("s_waitcnt lgkmcnt(" #n ")" ::: "memory")
; #define PG8_BAR __builtin_amdgcn_s_barrier()
; #define PG8_SCHED __builtin_amdgcn_sched_barrier(0)
; template <class Epi, class Sched>
; DI void gemm_phase(ldsp lds, const Gemm g, const Sched& S, const Epi& E, const int tid) {
;     ...
;             PG8_WAIT_V(6); PG8_BAR; PG8_MMA(1, 1, At, B1); PG8_BAR;
;             PG8_LDB(B0, 1, 0); PG8_SCHED; PG8_LDA(At, 1, 0); PG8_STAGE(PG8_SA(0, 1), a2 + hstep, voffA);
;             PG8_WAIT_L(8); PG8_BAR; PG8_WAIT_L(0); PG8_MMA(0, 0, At, B0); PG8_BAR; PG8_SCHED;
;             PG8_LDB(B1, 1, 1); PG8_STAGE(PG8_SB(1, 0), b3, voffB);
;             PG8_BAR; PG8_WAIT_L(0); PG8_MMA(0, 1, At, B1); PG8_BAR;
;             PG8_LDA(At, 1, 1); PG8_STAGE(PG8_SA(1, 0), a3, voffA);
;             PG8_BAR; PG8_WAIT_L(0); PG8_MMA(1, 0, At, B0); PG8_BAR; PG8_SCHED;
	s_add_u32 s72, s48, 0x40000
	s_addc_u32 s73, s49, 0
	s_add_i32 s74, s74, s35
	v_lshl_add_u64 v[146:147], s[72:73], 0, v[136:137]
	s_mov_b32 m0, s74
	s_nop 0
	global_load_lds_dwordx4 v[146:147], off
	v_lshl_add_u64 v[146:147], s[72:73], 0, v[30:31]
	s_add_i32 m0, s74, 0x2000
	s_nop 0
	global_load_lds_dwordx4 v[146:147], off
	s_waitcnt vmcnt(6)
	s_barrier
	s_setprio 1
	v_mfma_f32_16x16x32_bf16 v[50:53], v[202:205], v[170:173], v[50:53]
	v_mfma_f32_16x16x32_bf16 v[46:49], v[210:213], v[170:173], v[46:49]
	v_mfma_f32_16x16x32_bf16 v[34:37], v[202:205], v[178:181], v[34:37]
	v_mfma_f32_16x16x32_bf16 v[26:29], v[210:213], v[178:181], v[26:29]
	v_mfma_f32_16x16x32_bf16 v[14:17], v[202:205], v[186:189], v[14:17]
	v_mfma_f32_16x16x32_bf16 v[8:11], v[210:213], v[186:189], v[8:11]
	v_mfma_f32_16x16x32_bf16 v[4:7], v[202:205], v[194:197], v[4:7]
	v_mfma_f32_16x16x32_bf16 v[0:3], v[210:213], v[194:197], v[0:3]
	v_mfma_f32_16x16x32_bf16 v[50:53], v[206:209], v[174:177], v[50:53]
	v_mfma_f32_16x16x32_bf16 v[46:49], v[214:217], v[174:177], v[46:49]
	v_mfma_f32_16x16x32_bf16 v[34:37], v[206:209], v[182:185], v[34:37]
	v_mfma_f32_16x16x32_bf16 v[26:29], v[214:217], v[182:185], v[26:29]
	v_mfma_f32_16x16x32_bf16 v[14:17], v[206:209], v[190:193], v[14:17]
	v_mfma_f32_16x16x32_bf16 v[8:11], v[214:217], v[190:193], v[8:11]
	v_mfma_f32_16x16x32_bf16 v[4:7], v[206:209], v[198:201], v[4:7]
	v_mfma_f32_16x16x32_bf16 v[0:3], v[214:217], v[198:201], v[0:3]
	s_setprio 0
	s_add_i32 s72, 0, 0x18000
	v_add_u32_e32 v156, s72, v33
	s_barrier
	ds_read_b128 v[146:149], v156
	ds_read_b128 v[150:153], v156 offset:1024
	ds_read_b128 v[162:165], v156 offset:2048
	ds_read_b128 v[166:169], v156 offset:3072
	s_add_u32 s50, s50, 0x40000
	s_addc_u32 s51, s51, 0
	s_mov_b32 m0, s59
	v_lshl_add_u64 v[202:203], s[50:51], 0, v[138:139]
	ds_read_b128 v[170:173], v145 offset:32768
	ds_read_b128 v[174:177], v145 offset:33792
	ds_read_b128 v[178:181], v145 offset:34816
	ds_read_b128 v[182:185], v145 offset:35840
	ds_read_b128 v[186:189], v145 offset:36864
	ds_read_b128 v[190:193], v145 offset:37888
	ds_read_b128 v[194:197], v145 offset:38912
	ds_read_b128 v[198:201], v145 offset:39936
	global_load_lds_dwordx4 v[202:203], off
	v_lshl_add_u64 v[202:203], s[50:51], 0, v[134:135]
	s_mov_b32 m0, s60
	s_nop 0
	global_load_lds_dwordx4 v[202:203], off
	s_waitcnt lgkmcnt(8)
	s_barrier
	s_waitcnt lgkmcnt(0)
	s_setprio 1
	s_waitcnt lgkmcnt(0)
	v_mfma_f32_16x16x32_bf16 v[130:133], v[146:149], v[170:173], v[130:133]
	v_mfma_f32_16x16x32_bf16 v[126:129], v[162:165], v[170:173], v[126:129]
	v_mfma_f32_16x16x32_bf16 v[122:125], v[146:149], v[178:181], v[122:125]
	v_mfma_f32_16x16x32_bf16 v[118:121], v[162:165], v[178:181], v[118:121]
	v_mfma_f32_16x16x32_bf16 v[106:109], v[146:149], v[186:189], v[106:109]
	v_mfma_f32_16x16x32_bf16 v[102:105], v[162:165], v[186:189], v[102:105]
	v_mfma_f32_16x16x32_bf16 v[90:93], v[146:149], v[194:197], v[90:93]
	v_mfma_f32_16x16x32_bf16 v[86:89], v[162:165], v[194:197], v[86:89]
	v_mfma_f32_16x16x32_bf16 v[130:133], v[150:153], v[174:177], v[130:133]
	v_mfma_f32_16x16x32_bf16 v[126:129], v[166:169], v[174:177], v[126:129]
	v_mfma_f32_16x16x32_bf16 v[122:125], v[150:153], v[182:185], v[122:125]
	v_mfma_f32_16x16x32_bf16 v[118:121], v[166:169], v[182:185], v[118:121]
	v_mfma_f32_16x16x32_bf16 v[106:109], v[150:153], v[190:193], v[106:109]
	v_mfma_f32_16x16x32_bf16 v[102:105], v[166:169], v[190:193], v[102:105]
	v_mfma_f32_16x16x32_bf16 v[90:93], v[150:153], v[198:201], v[90:93]
	v_mfma_f32_16x16x32_bf16 v[86:89], v[166:169], v[198:201], v[86:89]
	s_setprio 0
	s_barrier
	s_add_i32 s50, 0, 0x1c000
	s_add_i32 s51, s72, s35
	v_add_u32_e32 v156, s50, v33
	v_lshl_add_u64 v[158:159], v[158:159], 0, s[96:97]
	s_mov_b32 m0, s51
	ds_read_b128 v[202:205], v156
	ds_read_b128 v[206:209], v156 offset:1024
	ds_read_b128 v[210:213], v156 offset:2048
	ds_read_b128 v[214:217], v156 offset:3072
	global_load_lds_dwordx4 v[158:159], off
	v_lshl_add_u64 v[158:159], v[160:161], 0, s[96:97]
	s_add_i32 m0, s51, 0x2000
	s_nop 0
	global_load_lds_dwordx4 v[158:159], off
	s_barrier
	s_waitcnt lgkmcnt(0)
	s_setprio 1
	s_waitcnt lgkmcnt(0)
	v_mfma_f32_16x16x32_bf16 v[114:117], v[202:205], v[170:173], v[114:117]
	v_mfma_f32_16x16x32_bf16 v[110:113], v[210:213], v[170:173], v[110:113]
	v_mfma_f32_16x16x32_bf16 v[98:101], v[202:205], v[178:181], v[98:101]
	v_mfma_f32_16x16x32_bf16 v[94:97], v[210:213], v[178:181], v[94:97]
	v_mfma_f32_16x16x32_bf16 v[82:85], v[202:205], v[186:189], v[82:85]
	v_mfma_f32_16x16x32_bf16 v[78:81], v[210:213], v[186:189], v[78:81]
	v_mfma_f32_16x16x32_bf16 v[74:77], v[202:205], v[194:197], v[74:77]
	v_mfma_f32_16x16x32_bf16 v[70:73], v[210:213], v[194:197], v[70:73]
	v_mfma_f32_16x16x32_bf16 v[114:117], v[206:209], v[174:177], v[114:117]
	v_mfma_f32_16x16x32_bf16 v[110:113], v[214:217], v[174:177], v[110:113]
	v_mfma_f32_16x16x32_bf16 v[98:101], v[206:209], v[182:185], v[98:101]
	v_mfma_f32_16x16x32_bf16 v[94:97], v[214:217], v[182:185], v[94:97]
	v_mfma_f32_16x16x32_bf16 v[82:85], v[206:209], v[190:193], v[82:85]
	v_mfma_f32_16x16x32_bf16 v[78:81], v[214:217], v[190:193], v[78:81]
	v_mfma_f32_16x16x32_bf16 v[74:77], v[206:209], v[198:201], v[74:77]
	v_mfma_f32_16x16x32_bf16 v[70:73], v[214:217], v[198:201], v[70:73]
	s_setprio 0
	s_mov_b32 m0, s62
	v_lshl_add_u64 v[158:159], v[218:219], 0, s[96:97]
	s_barrier
	ds_read_b128 v[170:173], v145 offset:49152
	ds_read_b128 v[174:177], v145 offset:50176
	ds_read_b128 v[178:181], v145 offset:51200
	ds_read_b128 v[182:185], v145 offset:52224
	ds_read_b128 v[186:189], v145 offset:53248
	ds_read_b128 v[190:193], v145 offset:54272
	ds_read_b128 v[194:197], v145 offset:55296
	ds_read_b128 v[198:201], v145 offset:56320
	global_load_lds_dwordx4 v[158:159], off
	v_lshl_add_u64 v[158:159], v[220:221], 0, s[96:97]
	s_mov_b32 m0, s63
	s_nop 0
	global_load_lds_dwordx4 v[158:159], off
	s_barrier
; DI unsigned cvt_pk_bf16(float lo, float hi) { const f32x2_t v = {lo, hi}; const bf16v2_t b = __builtin_convertvector(v, bf16v2_t); return __builtin_bit_cast(unsigned, b); }
; #define PG8_STAGE(bufoff, gbase, voff) do { _Pragma("unroll") for (int _i = 0; _i < 2; ++_i) \
;         __builtin_amdgcn_global_load_lds((const unsigned*)((const char*)(gbase) + (voff)[_i]), (LAS unsigned*)(lds + (bufoff) + ldsw + _i * 8192), 16, 0, 0); } while (0)
; #define PG8_MMA(ai, bj, At, Bt) do { __builtin_amdgcn_s_setprio(1); _Pragma("unroll") for (int m = 0; m < 4; ++m) _Pragma("unroll") for (int n = 0; n < 2; ++n) _Pragma("unroll") for (int k = 0; k < 2; ++k) \
;         acc[ai][bj][m][n] = __builtin_amdgcn_mfma_f32_16x16x32_bf16(Bt[n][k], At[m][k], acc[ai][bj][m][n], 0, 0, 0); __builtin_amdgcn_s_setprio(0); } while (0)
; #define PG8_WAIT_V(n) asm volatile("s_waitcnt vmcnt(" #n ")" ::: "memory")
; #define PG8_WAIT_L(n) asm volatile("s_waitcnt lgkmcnt(" #n ")" ::: "memory")
; #define PG8_BAR __builtin_amdgcn_s_barrier()
; #define PG8_SCHED __builtin_amdgcn_sched_barrier(0)
;     DI void operator()(const f32x4 (&acc)[2][2][4][2], const Unit& u, int wr, int wc, int fr, int fq) const {
;         const int row0 = u.pm * BM + wr * 64 + fr; const int col0 = u.pn * BM + wc * 32 + 8 * fq;
; #pragma unroll
;         for (int ai = 0; ai < 2; ++ai)
; #pragma unroll
;             for (int m = 0; m < 4; ++m) { const int row = row0 + ai * HALF + m * 16; bf16_t* rowp = O + (size_t)row * ldc + col0;
; #pragma unroll
;                 for (int bj = 0; bj < 2; ++bj) { const f32x4 v0 = acc[ai][bj][m][0], v1 = acc[ai][bj][m][1];
;                     u32x4 w; w.x = cvt_pk_bf16(v0[0], v0[1]); w.y = cvt_pk_bf16(v0[2], v0[3]); w.z = cvt_pk_bf16(v1[0], v1[1]); w.w = cvt_pk_bf16(v1[2], v1[3]);
;                     *(u32x4*)(rowp + bj * HALF) = w; } }
;     }
; template <class Epi, class Sched>
; DI void gemm_phase(ldsp lds, const Gemm g, const Sched& S, const Epi& E, const int tid) {
;     ...
;             PG8_BAR; PG8_WAIT_L(0); PG8_MMA(1, 0, At, B0); PG8_BAR; PG8_SCHED;
;             PG8_STAGE(PG8_SB(1, 1), b3 + hstep, voffB);
;             PG8_WAIT_V(6); PG8_BAR; PG8_MMA(1, 1, At, B1); PG8_BAR;
;         }
;         E(acc, cur, wr, wc, fr, fq);
;         if (!has_next) break;
	s_waitcnt lgkmcnt(0)
	s_setprio 1
	s_waitcnt lgkmcnt(0)
	v_mfma_f32_16x16x32_bf16 v[66:69], v[146:149], v[170:173], v[66:69]
	v_mfma_f32_16x16x32_bf16 v[62:65], v[162:165], v[170:173], v[62:65]
	v_mfma_f32_16x16x32_bf16 v[58:61], v[146:149], v[178:181], v[58:61]
	v_mfma_f32_16x16x32_bf16 v[54:57], v[162:165], v[178:181], v[54:57]
	v_mfma_f32_16x16x32_bf16 v[42:45], v[146:149], v[186:189], v[42:45]
	v_mfma_f32_16x16x32_bf16 v[38:41], v[162:165], v[186:189], v[38:41]
	v_mfma_f32_16x16x32_bf16 v[22:25], v[146:149], v[194:197], v[22:25]
	v_mfma_f32_16x16x32_bf16 v[18:21], v[162:165], v[194:197], v[18:21]
	v_mfma_f32_16x16x32_bf16 v[66:69], v[150:153], v[174:177], v[66:69]
	v_mfma_f32_16x16x32_bf16 v[62:65], v[166:169], v[174:177], v[62:65]
	v_mfma_f32_16x16x32_bf16 v[58:61], v[150:153], v[182:185], v[58:61]
	v_mfma_f32_16x16x32_bf16 v[54:57], v[166:169], v[182:185], v[54:57]
	v_mfma_f32_16x16x32_bf16 v[42:45], v[150:153], v[190:193], v[42:45]
	v_mfma_f32_16x16x32_bf16 v[38:41], v[166:169], v[190:193], v[38:41]
	v_mfma_f32_16x16x32_bf16 v[22:25], v[150:153], v[198:201], v[22:25]
	v_mfma_f32_16x16x32_bf16 v[18:21], v[166:169], v[198:201], v[18:21]
	s_setprio 0
	s_barrier
	s_add_u32 s48, s48, 0x40080
	s_addc_u32 s49, s49, 0
	s_add_i32 s50, s50, s35
	v_lshl_add_u64 v[146:147], s[48:49], 0, v[136:137]
	s_mov_b32 m0, s50
	s_nop 0
	global_load_lds_dwordx4 v[146:147], off
	v_lshl_add_u64 v[146:147], s[48:49], 0, v[30:31]
	s_add_i32 m0, s50, 0x2000
	s_nop 0
	global_load_lds_dwordx4 v[146:147], off
	s_waitcnt vmcnt(6)
	s_barrier
	s_setprio 1
	v_mfma_f32_16x16x32_bf16 v[50:53], v[202:205], v[170:173], v[50:53]
	v_mfma_f32_16x16x32_bf16 v[46:49], v[210:213], v[170:173], v[46:49]
	v_mfma_f32_16x16x32_bf16 v[34:37], v[202:205], v[178:181], v[34:37]
	v_mfma_f32_16x16x32_bf16 v[26:29], v[210:213], v[178:181], v[26:29]
	v_mfma_f32_16x16x32_bf16 v[14:17], v[202:205], v[186:189], v[14:17]
	v_mfma_f32_16x16x32_bf16 v[8:11], v[210:213], v[186:189], v[8:11]
	v_mfma_f32_16x16x32_bf16 v[4:7], v[202:205], v[194:197], v[4:7]
	v_mfma_f32_16x16x32_bf16 v[0:3], v[210:213], v[194:197], v[0:3]
	v_mfma_f32_16x16x32_bf16 v[50:53], v[206:209], v[174:177], v[50:53]
	v_mfma_f32_16x16x32_bf16 v[46:49], v[214:217], v[174:177], v[46:49]
	v_mfma_f32_16x16x32_bf16 v[34:37], v[206:209], v[182:185], v[34:37]
	v_mfma_f32_16x16x32_bf16 v[26:29], v[214:217], v[182:185], v[26:29]
	v_mfma_f32_16x16x32_bf16 v[14:17], v[206:209], v[190:193], v[14:17]
	v_mfma_f32_16x16x32_bf16 v[8:11], v[214:217], v[190:193], v[8:11]
	v_mfma_f32_16x16x32_bf16 v[4:7], v[206:209], v[198:201], v[4:7]
	v_mfma_f32_16x16x32_bf16 v[0:3], v[214:217], v[198:201], v[0:3]
	s_setprio 0
	s_add_i32 s69, s69, 2
	s_add_u32 s46, s46, 0x100
	s_addc_u32 s47, s47, 0
	s_add_u32 s67, s67, 0x100
	s_addc_u32 s68, s68, 0
	s_cmp_gt_u32 s69, 13
	s_barrier
	s_cbranch_scc0 .LBB0_663
	s_cmp_lg_u64 s[38:39], 0
	s_cbranch_scc1 .Lg1_epi_last
	s_lshl_b32 s101, s30, 8
	s_mul_i32 s101, s101, s14
	s_lshl_b32 s99, s64, 8
	s_add_u32 s101, s101, s99
	s_lshl_b32 s101, s101, 1
	s_add_u32 s98, s26, s101
	s_addc_u32 s99, s27, 0
	v_cvt_pk_bf16_f32 v114, v114, v115
	v_cvt_pk_bf16_f32 v115, v116, v117
	v_cvt_pk_bf16_f32 v116, v110, v111
	v_cvt_pk_bf16_f32 v117, v112, v113
	global_store_dwordx4 v224, v[114:117], s[98:99] offset:256
	v_cvt_pk_bf16_f32 v130, v130, v131
	v_cvt_pk_bf16_f32 v131, v132, v133
	v_cvt_pk_bf16_f32 v132, v126, v127
	v_cvt_pk_bf16_f32 v133, v128, v129
	global_store_dwordx4 v224, v[130:133], s[98:99]
	s_mul_i32 s101, s100, 1
	v_add_u32_e32 v226, s101, v224
	v_cvt_pk_bf16_f32 v98, v98, v99
	v_cvt_pk_bf16_f32 v99, v100, v101
	v_cvt_pk_bf16_f32 v100, v94, v95
	v_cvt_pk_bf16_f32 v101, v96, v97
	global_store_dwordx4 v226, v[98:101], s[98:99] offset:256
	v_cvt_pk_bf16_f32 v122, v122, v123
	v_cvt_pk_bf16_f32 v123, v124, v125
	v_cvt_pk_bf16_f32 v124, v118, v119
	v_cvt_pk_bf16_f32 v125, v120, v121
	global_store_dwordx4 v226, v[122:125], s[98:99]
	s_mul_i32 s101, s100, 2
	v_add_u32_e32 v225, s101, v224
	v_cvt_pk_bf16_f32 v82, v82, v83
	v_cvt_pk_bf16_f32 v83, v84, v85
	v_cvt_pk_bf16_f32 v84, v78, v79
	v_cvt_pk_bf16_f32 v85, v80, v81
	global_store_dwordx4 v225, v[82:85], s[98:99] offset:256
	v_cvt_pk_bf16_f32 v106, v106, v107
	v_cvt_pk_bf16_f32 v107, v108, v109
	v_cvt_pk_bf16_f32 v108, v102, v103
	v_cvt_pk_bf16_f32 v109, v104, v105
	global_store_dwordx4 v225, v[106:109], s[98:99]
	s_mul_i32 s101, s100, 3
	v_add_u32_e32 v226, s101, v224
	v_cvt_pk_bf16_f32 v74, v74, v75
	v_cvt_pk_bf16_f32 v75, v76, v77
	v_cvt_pk_bf16_f32 v76, v70, v71
	v_cvt_pk_bf16_f32 v77, v72, v73
	global_store_dwordx4 v226, v[74:77], s[98:99] offset:256
	v_cvt_pk_bf16_f32 v90, v90, v91
	v_cvt_pk_bf16_f32 v91, v92, v93
	v_cvt_pk_bf16_f32 v92, v86, v87
	v_cvt_pk_bf16_f32 v93, v88, v89
	global_store_dwordx4 v226, v[90:93], s[98:99]
	s_mul_i32 s101, s100, 8
	v_add_u32_e32 v225, s101, v224
	v_cvt_pk_bf16_f32 v50, v50, v51
	v_cvt_pk_bf16_f32 v51, v52, v53
	v_cvt_pk_bf16_f32 v52, v46, v47
	v_cvt_pk_bf16_f32 v53, v48, v49
	global_store_dwordx4 v225, v[50:53], s[98:99] offset:256
	v_cvt_pk_bf16_f32 v66, v66, v67
	v_cvt_pk_bf16_f32 v67, v68, v69
	v_cvt_pk_bf16_f32 v68, v62, v63
	v_cvt_pk_bf16_f32 v69, v64, v65
	global_store_dwordx4 v225, v[66:69], s[98:99]
	s_mul_i32 s101, s100, 9
	v_add_u32_e32 v226, s101, v224
	v_cvt_pk_bf16_f32 v34, v34, v35
	v_cvt_pk_bf16_f32 v35, v36, v37
	v_cvt_pk_bf16_f32 v36, v26, v27
	v_cvt_pk_bf16_f32 v37, v28, v29
	global_store_dwordx4 v226, v[34:37], s[98:99] offset:256
	v_cvt_pk_bf16_f32 v58, v58, v59
	v_cvt_pk_bf16_f32 v59, v60, v61
	v_cvt_pk_bf16_f32 v60, v54, v55
	v_cvt_pk_bf16_f32 v61, v56, v57
	global_store_dwordx4 v226, v[58:61], s[98:99]
	s_mul_i32 s101, s100, 10
	v_add_u32_e32 v225, s101, v224
	v_cvt_pk_bf16_f32 v14, v14, v15
	v_cvt_pk_bf16_f32 v15, v16, v17
	v_cvt_pk_bf16_f32 v16, v8, v9
	v_cvt_pk_bf16_f32 v17, v10, v11
	global_store_dwordx4 v225, v[14:17], s[98:99] offset:256
	v_cvt_pk_bf16_f32 v42, v42, v43
	v_cvt_pk_bf16_f32 v43, v44, v45
	v_cvt_pk_bf16_f32 v44, v38, v39
	v_cvt_pk_bf16_f32 v45, v40, v41
	global_store_dwordx4 v225, v[42:45], s[98:99]
	s_mul_i32 s101, s100, 11
	v_add_u32_e32 v226, s101, v224
	v_cvt_pk_bf16_f32 v4, v4, v5
	v_cvt_pk_bf16_f32 v5, v6, v7
	v_cvt_pk_bf16_f32 v6, v0, v1
	v_cvt_pk_bf16_f32 v7, v2, v3
	global_store_dwordx4 v226, v[4:7], s[98:99] offset:256
	v_cvt_pk_bf16_f32 v22, v22, v23
	v_cvt_pk_bf16_f32 v23, v24, v25
	v_cvt_pk_bf16_f32 v24, v18, v19
	v_cvt_pk_bf16_f32 v25, v20, v21
	global_store_dwordx4 v226, v[22:25], s[98:99]
; DI unsigned cvt_pk_bf16(float lo, float hi) { const f32x2_t v = {lo, hi}; const bf16v2_t b = __builtin_convertvector(v, bf16v2_t); return __builtin_bit_cast(unsigned, b); }
; #define PG8_WAIT_V(n) asm volatile("s_waitcnt vmcnt(" #n ")" ::: "memory")
; #define PG8_BAR __builtin_amdgcn_s_barrier()
;     DI void operator()(const f32x4 (&acc)[2][2][4][2], const Unit& u, int wr, int wc, int fr, int fq) const {
;     ...
;             for (int m = 0; m < 4; ++m) { const int row = row0 + ai * HALF + m * 16; bf16_t* rowp = O + (size_t)row * ldc + col0;
; #pragma unroll
;                 for (int bj = 0; bj < 2; ++bj) { const f32x4 v0 = acc[ai][bj][m][0], v1 = acc[ai][bj][m][1];
;                     u32x4 w; w.x = cvt_pk_bf16(v0[0], v0[1]); w.y = cvt_pk_bf16(v0[2], v0[3]); w.z = cvt_pk_bf16(v1[0], v1[1]); w.w = cvt_pk_bf16(v1[2], v1[3]);
;                     *(u32x4*)(rowp + bj * HALF) = w; } }
; template <class Epi, class Sched>
; DI void gemm_phase(ldsp lds, const Gemm g, const Sched& S, const Epi& E, const int tid) {
;     ...
;         E(acc, cur, wr, wc, fr, fq);
;         if (!has_next) break;
; #pragma unroll
;         for (int a = 0; a < 2; ++a)
; #pragma unroll
;             for (int b = 0; b < 2; ++b)
; #pragma unroll
;                 for (int m = 0; m < 4; ++m)
; #pragma unroll
;                     for (int n = 0; n < 2; ++n) acc[a][b][m][n] = (f32x4){0.f, 0.f, 0.f, 0.f};
;         cur = nxt; cA = nA; cB = nB; ++ui;
;     }
;     PG8_WAIT_V(0);
;     if (wr == 0) PG8_BAR;
;     PG8_BAR;
.Lg1_epi_join:
	s_and_b64 vcc, exec, s[38:39]
	s_mov_b32 s64, s36
	s_mov_b32 s30, s40
	s_mov_b64 s[48:49], s[44:45]
	s_mov_b64 s[46:47], s[42:43]
	v_readlane_b32 s78, v254, 54
	s_cbranch_vccz .LBB0_660
	s_branch .Lg1_epi_skip
.Lg1_epi_last:
	s_lshl_b32 s101, s30, 8
	s_mul_i32 s101, s101, s14
	s_lshl_b32 s99, s64, 8
	s_add_u32 s101, s101, s99
	s_lshl_b32 s101, s101, 1
	s_add_u32 s98, s26, s101
	s_addc_u32 s99, s27, 0
	v_cvt_pk_bf16_f32 v114, v114, v115
	v_cvt_pk_bf16_f32 v115, v116, v117
	v_cvt_pk_bf16_f32 v116, v110, v111
	v_cvt_pk_bf16_f32 v117, v112, v113
	global_store_dwordx4 v224, v[114:117], s[98:99] offset:256 sc1
	v_cvt_pk_bf16_f32 v130, v130, v131
	v_cvt_pk_bf16_f32 v131, v132, v133
	v_cvt_pk_bf16_f32 v132, v126, v127
	v_cvt_pk_bf16_f32 v133, v128, v129
	global_store_dwordx4 v224, v[130:133], s[98:99] sc1
	s_mul_i32 s101, s100, 1
	v_add_u32_e32 v226, s101, v224
	v_cvt_pk_bf16_f32 v98, v98, v99
	v_cvt_pk_bf16_f32 v99, v100, v101
	v_cvt_pk_bf16_f32 v100, v94, v95
	v_cvt_pk_bf16_f32 v101, v96, v97
	global_store_dwordx4 v226, v[98:101], s[98:99] offset:256 sc1
	v_cvt_pk_bf16_f32 v122, v122, v123
	v_cvt_pk_bf16_f32 v123, v124, v125
	v_cvt_pk_bf16_f32 v124, v118, v119
	v_cvt_pk_bf16_f32 v125, v120, v121
	global_store_dwordx4 v226, v[122:125], s[98:99] sc1
	s_mul_i32 s101, s100, 2
	v_add_u32_e32 v225, s101, v224
	v_cvt_pk_bf16_f32 v82, v82, v83
	v_cvt_pk_bf16_f32 v83, v84, v85
	v_cvt_pk_bf16_f32 v84, v78, v79
	v_cvt_pk_bf16_f32 v85, v80, v81
	global_store_dwordx4 v225, v[82:85], s[98:99] offset:256 sc1
	v_cvt_pk_bf16_f32 v106, v106, v107
	v_cvt_pk_bf16_f32 v107, v108, v109
	v_cvt_pk_bf16_f32 v108, v102, v103
	v_cvt_pk_bf16_f32 v109, v104, v105
	global_store_dwordx4 v225, v[106:109], s[98:99] sc1
	s_mul_i32 s101, s100, 3
	v_add_u32_e32 v226, s101, v224
	v_cvt_pk_bf16_f32 v74, v74, v75
	v_cvt_pk_bf16_f32 v75, v76, v77
	v_cvt_pk_bf16_f32 v76, v70, v71
	v_cvt_pk_bf16_f32 v77, v72, v73
	global_store_dwordx4 v226, v[74:77], s[98:99] offset:256 sc1
	v_cvt_pk_bf16_f32 v90, v90, v91
	v_cvt_pk_bf16_f32 v91, v92, v93
	v_cvt_pk_bf16_f32 v92, v86, v87
	v_cvt_pk_bf16_f32 v93, v88, v89
	global_store_dwordx4 v226, v[90:93], s[98:99] sc1
	s_mul_i32 s101, s100, 8
	v_add_u32_e32 v225, s101, v224
	v_cvt_pk_bf16_f32 v50, v50, v51
	v_cvt_pk_bf16_f32 v51, v52, v53
	v_cvt_pk_bf16_f32 v52, v46, v47
	v_cvt_pk_bf16_f32 v53, v48, v49
	global_store_dwordx4 v225, v[50:53], s[98:99] offset:256 sc1
	v_cvt_pk_bf16_f32 v66, v66, v67
	v_cvt_pk_bf16_f32 v67, v68, v69
	v_cvt_pk_bf16_f32 v68, v62, v63
	v_cvt_pk_bf16_f32 v69, v64, v65
	global_store_dwordx4 v225, v[66:69], s[98:99] sc1
	s_mul_i32 s101, s100, 9
	v_add_u32_e32 v226, s101, v224
	v_cvt_pk_bf16_f32 v34, v34, v35
	v_cvt_pk_bf16_f32 v35, v36, v37
	v_cvt_pk_bf16_f32 v36, v26, v27
	v_cvt_pk_bf16_f32 v37, v28, v29
	global_store_dwordx4 v226, v[34:37], s[98:99] offset:256 sc1
	v_cvt_pk_bf16_f32 v58, v58, v59
	v_cvt_pk_bf16_f32 v59, v60, v61
	v_cvt_pk_bf16_f32 v60, v54, v55
	v_cvt_pk_bf16_f32 v61, v56, v57
	global_store_dwordx4 v226, v[58:61], s[98:99] sc1
	s_mul_i32 s101, s100, 10
	v_add_u32_e32 v225, s101, v224
	v_cvt_pk_bf16_f32 v14, v14, v15
	v_cvt_pk_bf16_f32 v15, v16, v17
	v_cvt_pk_bf16_f32 v16, v8, v9
	v_cvt_pk_bf16_f32 v17, v10, v11
	global_store_dwordx4 v225, v[14:17], s[98:99] offset:256 sc1
	v_cvt_pk_bf16_f32 v42, v42, v43
	v_cvt_pk_bf16_f32 v43, v44, v45
	v_cvt_pk_bf16_f32 v44, v38, v39
	v_cvt_pk_bf16_f32 v45, v40, v41
	global_store_dwordx4 v225, v[42:45], s[98:99] sc1
	s_mul_i32 s101, s100, 11
	v_add_u32_e32 v226, s101, v224
	v_cvt_pk_bf16_f32 v4, v4, v5
	v_cvt_pk_bf16_f32 v5, v6, v7
	v_cvt_pk_bf16_f32 v6, v0, v1
	v_cvt_pk_bf16_f32 v7, v2, v3
	global_store_dwordx4 v226, v[4:7], s[98:99] offset:256 sc1
	v_cvt_pk_bf16_f32 v22, v22, v23
	v_cvt_pk_bf16_f32 v23, v24, v25
	v_cvt_pk_bf16_f32 v24, v18, v19
	v_cvt_pk_bf16_f32 v25, v20, v21
	global_store_dwordx4 v226, v[22:25], s[98:99] sc1
	s_branch .Lg1_epi_join
.Lg1_epi_skip:
	s_waitcnt vmcnt(0)
	v_readlane_b32 s72, v254, 58
	s_cmpk_gt_u32 s15, 0xff
	v_readlane_b32 s73, v254, 59
	s_cbranch_scc1 .LBB0_667
	s_barrier
